# as v8 plus nt on the read-once RWKV scan staging loads
# baseline (speedup 1.0000x reference)
.LBB0_1068:
	s_ashr_i32 s26, s40, 5
	s_lshl_b32 s8, s26, 2
	s_add_i32 s52, s8, 0x2000
	s_lshl_b32 s8, s40, 6
	s_and_b32 s8, s8, 0x7c0
	v_or_b32_e32 v89, s8, v80
	s_mov_b64 s[8:9], -1
	s_and_b64 vcc, exec, s[10:11]
	s_cbranch_vccz .LBB0_1079
	v_readlane_b32 s72, v254, 28
	v_readlane_b32 s74, v254, 30
	v_readlane_b32 s75, v254, 31
	v_readlane_b32 s76, v254, 32
	v_readlane_b32 s77, v254, 33
	v_readlane_b32 s78, v254, 34
	v_readlane_b32 s79, v254, 35
	v_readlane_b32 s80, v254, 36
	v_readlane_b32 s81, v254, 37
	v_readlane_b32 s82, v254, 38
	v_readlane_b32 s83, v254, 39
	v_lshlrev_b32_e32 v72, 2, v89
	v_readlane_b32 s84, v254, 40
	v_readlane_b32 s85, v254, 41
	v_readlane_b32 s86, v254, 42
	v_readlane_b32 s87, v254, 43
	s_mov_b64 s[74:75], s[78:79]
	s_mov_b64 s[76:77], s[80:81]
	global_load_dwordx4 v[24:27], v72, s[14:15] nt
	global_load_dwordx4 v[10:13], v72, s[18:19] nt
	global_load_dwordx4 v[32:35], v72, s[70:71] nt
	s_mov_b64 s[78:79], s[82:83]
	s_mov_b64 s[80:81], s[84:85]
	s_mov_b64 s[82:83], s[86:87]
	global_load_dwordx4 v[28:31], v72, s[74:75] nt
	global_load_dwordx4 v[6:9], v72, s[76:77] nt
	global_load_dwordx4 v[2:5], v72, s[78:79] nt
	global_load_dwordx4 v[16:19], v72, s[80:81] nt
	global_load_dwordx4 v[20:23], v72, s[82:83] nt
	v_mov_b32_e32 v47, 0
	s_waitcnt vmcnt(8)
	v_mov_b32_e32 v63, 0
	v_mov_b32_e32 v62, 0
	v_mov_b32_e32 v46, 0
	v_mov_b32_e32 v45, 0
	v_mov_b32_e32 v44, 0
	v_mov_b32_e32 v65, 0
	v_mov_b32_e32 v64, 0
	v_mov_b32_e32 v15, 0
	v_mov_b32_e32 v14, 0
	v_mov_b32_e32 v39, 0
	v_mov_b32_e32 v38, 0
	v_mov_b32_e32 v37, 0
	v_mov_b32_e32 v36, 0
	v_mov_b32_e32 v43, 0
	v_mov_b32_e32 v42, 0
	v_mov_b32_e32 v41, 0
	s_waitcnt lgkmcnt(0)
	v_mov_b32_e32 v40, 0
	v_mov_b32_e32 v51, 0
	v_mov_b32_e32 v50, 0
	v_mov_b32_e32 v49, 0
	v_mov_b32_e32 v48, 0
	v_mov_b32_e32 v69, 0
	v_mov_b32_e32 v68, 0
	v_mov_b32_e32 v67, 0
	v_mov_b32_e32 v66, 0
	v_mov_b32_e32 v75, 0
	v_mov_b32_e32 v74, 0
	v_mov_b32_e32 v71, 0
	v_mov_b32_e32 v70, 0
	v_mov_b32_e32 v77, 0
	v_mov_b32_e32 v76, 0
	v_mov_b32_e32 v79, 0
	v_mov_b32_e32 v78, 0
	v_readlane_b32 s73, v254, 29
	s_and_saveexec_b64 s[8:9], s[2:3]
	s_cbranch_execz .LBB0_1076
	v_add_u32_e32 v62, s52, v52
	v_mov_b64_e32 v[14:15], s[20:21]
	v_mad_i64_i32 v[14:15], s[42:43], v62, s59, v[14:15]
	v_lshlrev_b32_e32 v54, 1, v89
	v_lshl_add_u64 v[64:65], v[14:15], 0, v[54:55]
	v_add_co_u32_e32 v14, vcc, 0x1000, v64
	s_mov_b32 s41, s49
	s_nop 0
	v_addc_co_u32_e32 v15, vcc, 0, v65, vcc
	v_add_co_u32_e32 v36, vcc, 0x2000, v64
	s_nop 1
	v_addc_co_u32_e32 v37, vcc, 0, v65, vcc
	global_load_dwordx2 v[46:47], v[64:65], off nt
	global_load_dwordx2 v[44:45], v[14:15], off nt
	s_nop 0
	global_load_dwordx2 v[14:15], v[36:37], off nt
	s_and_saveexec_b64 s[42:43], s[4:5]
	s_xor_b64 s[54:55], exec, s[42:43]
	s_cbranch_execz .LBB0_1073
	s_andn2_b64 vcc, exec, s[22:23]
	s_cbranch_vccnz .LBB0_1093
	v_readlane_b32 s72, v254, 12
	v_readlane_b32 s84, v254, 24
	v_readlane_b32 s85, v254, 25
	s_mul_hi_i32 s27, s26, 0x6700
	s_mulk_i32 s26, 0x6700
	s_mov_b64 s[48:49], s[84:85]
	s_add_u32 s26, s48, s26
	s_addc_u32 s27, s49, s27
	v_mov_b32_e32 v73, v55
	v_lshl_add_u64 v[36:37], s[26:27], 0, v[72:73]
	v_add_co_u32_e32 v38, vcc, 0x2000, v36
	global_load_dwordx4 v[48:51], v72, s[26:27] nt
	s_nop 0
	v_addc_co_u32_e32 v39, vcc, 0, v37, vcc
	v_add_co_u32_e32 v36, vcc, 0x4000, v36
	v_readlane_b32 s73, v254, 13
	s_nop 0
	v_addc_co_u32_e32 v37, vcc, 0, v37, vcc
	global_load_dwordx4 v[40:43], v[38:39], off nt
	s_nop 0
	global_load_dwordx4 v[36:39], v[36:37], off nt
	v_readlane_b32 s74, v254, 14
	v_readlane_b32 s75, v254, 15
	v_readlane_b32 s76, v254, 16
	v_readlane_b32 s77, v254, 17
	v_readlane_b32 s78, v254, 18
	v_readlane_b32 s79, v254, 19
	v_readlane_b32 s80, v254, 20
	v_readlane_b32 s81, v254, 21
	v_readlane_b32 s82, v254, 22
	v_readlane_b32 s83, v254, 23
	v_readlane_b32 s86, v254, 26
	v_readlane_b32 s87, v254, 27

.LBB0_1074:
	s_waitcnt vmcnt(0)
	v_add_co_u32_e32 v36, vcc, 0xffffd000, v64
	s_nop 1
	v_addc_co_u32_e32 v37, vcc, -1, v65, vcc
	v_add_co_u32_e32 v38, vcc, 0xffffe000, v64
	global_load_dwordx2 v[36:37], v[36:37], off offset:-1024 nt
	s_nop 0
	v_addc_co_u32_e32 v39, vcc, -1, v65, vcc
	v_add_co_u32_e32 v40, vcc, 0xfffff000, v64
	global_load_dwordx2 v[38:39], v[38:39], off offset:-1024 nt
	s_nop 0
	v_addc_co_u32_e32 v41, vcc, -1, v65, vcc
	global_load_dwordx2 v[64:65], v[40:41], off offset:-1024 nt
	s_waitcnt vmcnt(2)
	v_lshlrev_b32_e32 v48, 16, v36
	v_and_b32_e32 v49, 0xffff0000, v36
	v_lshlrev_b32_e32 v50, 16, v37
	v_and_b32_e32 v51, 0xffff0000, v37
	s_waitcnt vmcnt(1)
	v_lshlrev_b32_e32 v40, 16, v38
	v_and_b32_e32 v41, 0xffff0000, v38
	v_lshlrev_b32_e32 v42, 16, v39
	v_and_b32_e32 v43, 0xffff0000, v39
	s_waitcnt vmcnt(0)
	v_lshlrev_b32_e32 v36, 16, v64
	v_and_b32_e32 v37, 0xffff0000, v64
	v_lshlrev_b32_e32 v38, 16, v65
	v_and_b32_e32 v39, 0xffff0000, v65
.LBB0_1075:
	s_or_b64 exec, exec, s[54:55]
	v_ashrrev_i32_e32 v63, 31, v62
	v_lshlrev_b64 v[62:63], 12, v[62:63]
	v_lshl_add_u64 v[64:65], s[24:25], 0, v[62:63]
	v_lshl_add_u64 v[64:65], v[64:65], 0, v[54:55]
	v_lshl_add_u64 v[66:67], s[28:29], 0, v[62:63]
	v_lshl_add_u64 v[66:67], v[66:67], 0, v[54:55]
	global_load_dwordx2 v[64:65], v[64:65], off nt
	s_nop 0
	global_load_dwordx2 v[72:73], v[66:67], off nt
	v_lshl_add_u64 v[62:63], s[30:31], 0, v[62:63]
	v_lshl_add_u64 v[62:63], v[62:63], 0, v[54:55]
	global_load_dwordx2 v[62:63], v[62:63], off nt
	s_waitcnt vmcnt(5)
	v_lshlrev_b32_e32 v78, 16, v46
	v_and_b32_e32 v79, 0xffff0000, v46
	v_lshlrev_b32_e32 v76, 16, v47
	v_and_b32_e32 v77, 0xffff0000, v47
	s_waitcnt vmcnt(4)
	v_lshlrev_b32_e32 v74, 16, v45
	v_and_b32_e32 v75, 0xffff0000, v45
	s_waitcnt vmcnt(3)
	v_lshlrev_b32_e32 v68, 16, v15
	v_and_b32_e32 v69, 0xffff0000, v15
	v_lshlrev_b32_e32 v70, 16, v44
	v_and_b32_e32 v71, 0xffff0000, v44
	v_lshlrev_b32_e32 v66, 16, v14
	v_and_b32_e32 v67, 0xffff0000, v14
	s_mov_b32 s49, s41
	s_waitcnt vmcnt(2)
	v_lshlrev_b32_e32 v14, 16, v64
	s_waitcnt vmcnt(1)
	v_lshlrev_b32_e32 v15, 16, v72
	v_and_b32_e32 v45, 0xffff0000, v72
	v_lshlrev_b32_e32 v46, 16, v73
	v_and_b32_e32 v47, 0xffff0000, v73
	v_exp_f32_e64 v44, -v15
	v_exp_f32_e64 v45, -v45
	v_exp_f32_e64 v46, -v46
	v_exp_f32_e64 v47, -v47
	v_and_b32_e32 v15, 0xffff0000, v64
	v_lshlrev_b32_e32 v64, 16, v65
	v_and_b32_e32 v65, 0xffff0000, v65

.LBB0_1148:
	s_lshl_b32 s14, s40, 6
	s_and_b32 s52, s14, 0xfffff800
	s_and_b32 s14, s14, 0x7c0
	v_or_b32_e32 v2, s14, v105
	v_mov_b32_e32 v75, v74
	s_and_b64 vcc, exec, s[10:11]
	v_lshlrev_b32_e32 v82, 1, v2
	v_mov_b64_e32 v[84:85], v[74:75]
	v_mov_b32_e32 v147, v74
	s_cbranch_vccnz .LBB0_1156
	v_readlane_b32 s72, v254, 28
	v_readlane_b32 s74, v254, 30
	v_readlane_b32 s75, v254, 31
	v_readlane_b32 s76, v254, 32
	v_readlane_b32 s77, v254, 33
	v_readlane_b32 s78, v254, 34
	v_readlane_b32 s79, v254, 35
	v_readlane_b32 s80, v254, 36
	v_readlane_b32 s81, v254, 37
	v_readlane_b32 s82, v254, 38
	v_readlane_b32 s83, v254, 39
	v_lshlrev_b32_e32 v2, 2, v2
	v_readlane_b32 s84, v254, 40
	v_readlane_b32 s85, v254, 41
	v_readlane_b32 s86, v254, 42
	v_readlane_b32 s87, v254, 43
	s_mov_b64 s[74:75], s[78:79]
	s_mov_b64 s[76:77], s[80:81]
	global_load_dwordx4 v[46:49], v2, s[18:19]
	global_load_dwordx4 v[42:45], v2, s[20:21]
	global_load_dwordx4 v[50:53], v2, s[70:71]
	s_mov_b64 s[78:79], s[82:83]
	s_mov_b64 s[80:81], s[84:85]
	s_mov_b64 s[82:83], s[86:87]
	global_load_dwordx4 v[62:65], v2, s[74:75]
	global_load_dwordx4 v[58:61], v2, s[76:77]
	global_load_dwordx4 v[54:57], v2, s[78:79]
	global_load_dwordx4 v[34:37], v2, s[80:81]
	s_waitcnt lgkmcnt(0)
	global_load_dwordx4 v[38:41], v2, s[82:83]
	v_add_u32_e32 v2, s52, v70
	v_mov_b64_e32 v[4:5], s[22:23]
	v_mad_i64_i32 v[4:5], s[14:15], v2, s56, v[4:5]
	v_mov_b32_e32 v83, v74
	v_lshl_add_u64 v[10:11], v[4:5], 0, v[82:83]
	v_add_co_u32_e32 v6, vcc, 0x1000, v10
	global_load_dwordx2 v[4:5], v[10:11], off nt
	s_nop 0
	v_addc_co_u32_e32 v7, vcc, 0, v11, vcc
	v_add_co_u32_e32 v12, vcc, 0x2000, v10
	v_mov_b32_e32 v19, 0
	s_nop 0
	v_addc_co_u32_e32 v13, vcc, 0, v11, vcc
	global_load_dwordx2 v[8:9], v[6:7], off nt
	s_nop 0
	global_load_dwordx2 v[6:7], v[12:13], off nt
	v_mov_b32_e32 v21, 0
	v_mov_b32_e32 v22, 0
	v_mov_b32_e32 v23, 0
	v_mov_b32_e32 v16, 0
	v_mov_b32_e32 v18, 0
	v_mov_b32_e32 v17, 0
	v_mov_b32_e32 v20, 0
	v_mov_b32_e32 v12, 0
	v_mov_b32_e32 v14, 0
	v_mov_b32_e32 v13, 0
	v_mov_b32_e32 v15, 0
	v_readlane_b32 s73, v254, 29
	s_and_saveexec_b64 s[14:15], s[2:3]
	s_cbranch_execz .LBB0_1151
	v_add_co_u32_e32 v12, vcc, 0xffffd000, v10
	s_nop 1
	v_addc_co_u32_e32 v13, vcc, -1, v11, vcc
	v_add_co_u32_e32 v14, vcc, 0xffffe000, v10
	global_load_dwordx2 v[12:13], v[12:13], off offset:-1024 nt
	s_nop 0
	v_addc_co_u32_e32 v15, vcc, -1, v11, vcc
	v_add_co_u32_e32 v10, vcc, 0xfffff000, v10
	global_load_dwordx2 v[14:15], v[14:15], off offset:-1024 nt
	s_nop 0
	v_addc_co_u32_e32 v11, vcc, -1, v11, vcc
	global_load_dwordx2 v[10:11], v[10:11], off offset:-1024 nt
	s_waitcnt vmcnt(2)
	v_lshlrev_b32_e32 v19, 16, v12
	v_and_b32_e32 v21, 0xffff0000, v12
	v_lshlrev_b32_e32 v22, 16, v13
	v_and_b32_e32 v23, 0xffff0000, v13
	s_waitcnt vmcnt(1)
	v_lshlrev_b32_e32 v16, 16, v14
	v_and_b32_e32 v18, 0xffff0000, v14
	v_lshlrev_b32_e32 v17, 16, v15
	v_and_b32_e32 v20, 0xffff0000, v15
	s_waitcnt vmcnt(0)
	v_lshlrev_b32_e32 v12, 16, v10
	v_and_b32_e32 v14, 0xffff0000, v10
	v_lshlrev_b32_e32 v13, 16, v11
	v_and_b32_e32 v15, 0xffff0000, v11
.LBB0_1151:
	s_or_b64 exec, exec, s[14:15]
	v_ashrrev_i32_e32 v3, 31, v2
	v_lshlrev_b64 v[10:11], 12, v[2:3]
	v_lshl_add_u64 v[24:25], s[24:25], 0, v[10:11]
	v_lshl_add_u64 v[24:25], v[24:25], 0, v[82:83]
	global_load_dwordx2 v[24:25], v[24:25], off nt
	v_lshl_add_u64 v[26:27], s[28:29], 0, v[10:11]
	v_lshl_add_u64 v[26:27], v[26:27], 0, v[82:83]
	global_load_dwordx2 v[26:27], v[26:27], off nt
	v_lshl_add_u64 v[10:11], s[30:31], 0, v[10:11]
	v_lshl_add_u64 v[10:11], v[10:11], 0, v[82:83]
	global_load_dwordx2 v[84:85], v[10:11], off nt
	s_waitcnt vmcnt(5)
	v_lshlrev_b32_e32 v10, 16, v4
	v_and_b32_e32 v11, 0xffff0000, v4
	s_waitcnt vmcnt(4)
	v_lshlrev_b32_e32 v28, 16, v8
	v_and_b32_e32 v29, 0xffff0000, v8
	v_lshlrev_b32_e32 v8, 16, v9
	v_and_b32_e32 v9, 0xffff0000, v9
	s_waitcnt vmcnt(3)
	v_lshlrev_b32_e32 v30, 16, v6
	v_and_b32_e32 v31, 0xffff0000, v6
	v_lshlrev_b32_e32 v6, 16, v7
	v_sub_f32_e32 v33, v21, v11
	v_sub_f32_e32 v32, v19, v10
	v_sub_f32_e32 v19, v18, v29
	v_sub_f32_e32 v18, v16, v28
	v_sub_f32_e32 v21, v20, v9
	v_sub_f32_e32 v20, v17, v8
	v_sub_f32_e32 v17, v14, v31
	v_sub_f32_e32 v16, v12, v30
	v_sub_f32_e32 v14, v13, v6
	v_pk_fma_f32 v[12:13], v[48:49], v[20:21], v[8:9]
	v_pk_fma_f32 v[18:19], v[46:47], v[18:19], v[28:29]
	v_pk_mul_f32 v[28:29], v[64:65], v[12:13]
	v_pk_mul_f32 v[66:67], v[62:63], v[18:19]
	v_pk_fma_f32 v[32:33], v[50:51], v[32:33], v[10:11]
	v_pk_mul_f32 v[8:9], v[28:29], v[28:29]
	v_pk_mul_f32 v[10:11], v[66:67], v[66:67]
	v_lshlrev_b32_e32 v4, 16, v5
	v_pk_mov_b32 v[20:21], v[10:11], v[8:9] op_sel:[1,0]
	v_mov_b32_e32 v11, v9
	v_pk_add_f32 v[8:9], v[20:21], v[10:11]
	v_and_b32_e32 v5, 0xffff0000, v5
	v_add_f32_e32 v3, v8, v9
	v_and_b32_e32 v7, 0xffff0000, v7
	v_sub_f32_e32 v23, v23, v5
	v_add_f32_dpp v3, v3, v3 quad_perm:[1,0,3,2] row_mask:0xf bank_mask:0xf bound_ctrl:1
	v_sub_f32_e32 v22, v22, v4
	v_sub_f32_e32 v15, v15, v7
	v_add_f32_dpp v3, v3, v3 quad_perm:[2,3,0,1] row_mask:0xf bank_mask:0xf bound_ctrl:1
	v_pk_fma_f32 v[68:69], v[52:53], v[22:23], v[4:5]
	v_pk_fma_f32 v[10:11], v[44:45], v[14:15], v[6:7]
	v_add_f32_dpp v3, v3, v3 row_half_mirror row_mask:0xf bank_mask:0xf bound_ctrl:1
	s_waitcnt vmcnt(1)
	v_lshlrev_b32_e32 v14, 16, v26
	v_add_f32_dpp v3, v3, v3 row_mirror row_mask:0xf bank_mask:0xf bound_ctrl:1
	v_mul_f32_e32 v8, 0x4f800000, v3
	v_cmp_gt_f32_e32 vcc, s60, v3
	v_and_b32_e32 v15, 0xffff0000, v26
	v_exp_f32_e64 v14, -v14
	v_cndmask_b32_e32 v3, v3, v8, vcc
	v_sqrt_f32_e32 v20, v3
	v_pk_fma_f32 v[8:9], v[42:43], v[16:17], v[30:31]
	v_lshlrev_b32_e32 v16, 16, v27
	v_and_b32_e32 v17, 0xffff0000, v27
	v_add_u32_e32 v4, -1, v20
	v_add_u32_e32 v5, 1, v20
	v_fma_f32 v6, -v4, v20, v3
	v_fma_f32 v7, -v5, v20, v3
	v_cmp_ge_f32_e64 s[14:15], 0, v6
	v_lshlrev_b32_e32 v6, 16, v25
	v_exp_f32_e64 v15, -v15
	v_cndmask_b32_e64 v4, v20, v4, s[14:15]
	v_cmp_lt_f32_e64 s[14:15], 0, v7
	v_and_b32_e32 v7, 0xffff0000, v25
	v_pk_add_f32 v[20:21], v[6:7], -1.0 op_sel_hi:[1,0]
	v_cndmask_b32_e64 v4, v4, v5, s[14:15]
	v_mul_f32_e32 v5, 0x37800000, v4
	v_cndmask_b32_e32 v4, v4, v5, vcc
	v_cmp_class_f32_e32 vcc, v3, v71
	v_and_b32_e32 v5, 0xffff0000, v24
	v_pk_fma_f32 v[20:21], v[60:61], v[20:21], 1.0 op_sel_hi:[1,1,0]
	v_cndmask_b32_e32 v3, v4, v3, vcc
	v_max_f32_e32 v3, 0x2b8cbccc, v3
	v_div_scale_f32 v30, s[14:15], v3, v3, -1.0
	v_lshlrev_b32_e32 v4, 16, v24
	v_rcp_f32_e32 v24, v30
	v_pk_mul_f32 v[20:21], v[12:13], v[20:21]
	v_pk_add_f32 v[22:23], v[4:5], -1.0 op_sel_hi:[1,0]
	v_exp_f32_e64 v16, -v16
	v_fma_f32 v12, -v30, v24, 1.0
	v_fmac_f32_e32 v24, v12, v24
	v_div_scale_f32 v12, vcc, -1.0, v3, -1.0
	v_pk_fma_f32 v[22:23], v[58:59], v[22:23], 1.0 op_sel_hi:[1,1,0]
	v_mul_f32_e32 v13, v12, v24
	v_pk_mul_f32 v[18:19], v[18:19], v[22:23]
	v_fma_f32 v22, -v30, v13, v12
	v_fmac_f32_e32 v13, v22, v24
	v_fma_f32 v12, -v30, v13, v12
	v_div_fmas_f32 v12, v12, v24, v13
	v_div_fixup_f32 v12, v12, v3, -1.0
	v_pk_mul_f32 v[22:23], v[66:67], v[12:13] op_sel_hi:[1,0]
	v_pk_mul_f32 v[24:25], v[28:29], v[12:13] op_sel_hi:[1,0]
	v_pk_mul_f32 v[26:27], v[22:23], v[4:5] neg_lo:[1,0] neg_hi:[1,0]
	v_pk_mul_f32 v[28:29], v[24:25], v[6:7] neg_lo:[1,0] neg_hi:[1,0]
	v_pk_mul_f32 v[6:7], v[32:33], v[26:27]
	v_pk_mul_f32 v[30:31], v[32:33], v[18:19]
	v_pk_mul_f32 v[4:5], v[68:69], v[28:29]
	v_pk_mul_f32 v[12:13], v[68:69], v[20:21]
	v_mov_b32_e32 v66, v6
	v_mov_b32_e32 v67, v30
	v_mov_b32_e32 v6, v7
	v_mov_b32_e32 v7, v31
	v_pk_add_f32 v[6:7], v[66:67], v[6:7]
	v_mov_b32_e32 v66, v4
	v_mov_b32_e32 v67, v12
	v_mov_b32_e32 v4, v5
	v_mov_b32_e32 v5, v13
	v_pk_add_f32 v[4:5], v[66:67], v[4:5]
	v_pk_mul_f32 v[12:13], v[56:57], v[12:13]
	v_pk_add_f32 v[4:5], v[6:7], v[4:5]
	v_mov_b32_e32 v6, v74
	v_mov_b32_e32 v7, v74
	v_pk_mul_f32 v[30:31], v[54:55], v[30:31]
	v_mov_b32_dpp v6, v4 quad_perm:[1,0,3,2] row_mask:0xf bank_mask:0xf
	v_mov_b32_dpp v7, v5 quad_perm:[1,0,3,2] row_mask:0xf bank_mask:0xf
	v_pk_add_f32 v[4:5], v[4:5], v[6:7]
	v_mov_b32_e32 v6, v74
	v_mov_b32_e32 v7, v74
	v_add_f32_e32 v3, v30, v31
	v_add_f32_e32 v12, v12, v13
	v_exp_f32_e64 v17, -v17
	v_mov_b32_dpp v6, v4 quad_perm:[2,3,0,1] row_mask:0xf bank_mask:0xf
	v_mov_b32_dpp v7, v5 quad_perm:[2,3,0,1] row_mask:0xf bank_mask:0xf
	v_add_f32_e32 v3, v3, v12
	v_pk_add_f32 v[4:5], v[4:5], v[6:7]
	v_mov_b32_e32 v6, v74
	v_mov_b32_e32 v7, v74
	v_add_f32_dpp v3, v3, v3 quad_perm:[1,0,3,2] row_mask:0xf bank_mask:0xf bound_ctrl:1
	v_mov_b32_dpp v6, v4 row_half_mirror row_mask:0xf bank_mask:0xf
	v_mov_b32_dpp v7, v5 row_half_mirror row_mask:0xf bank_mask:0xf
	v_add_f32_dpp v3, v3, v3 quad_perm:[2,3,0,1] row_mask:0xf bank_mask:0xf bound_ctrl:1
	v_pk_add_f32 v[4:5], v[4:5], v[6:7]
	v_mov_b32_e32 v6, v74
	v_mov_b32_e32 v7, v74
	v_add_f32_dpp v12, v3, v3 row_half_mirror row_mask:0xf bank_mask:0xf bound_ctrl:1
	v_mov_b32_e32 v13, v74
	v_mov_b32_dpp v6, v4 row_mirror row_mask:0xf bank_mask:0xf
	v_mov_b32_dpp v7, v5 row_mirror row_mask:0xf bank_mask:0xf
	v_mov_b32_dpp v13, v12 row_mirror row_mask:0xf bank_mask:0xf
	ds_write_b128 v127, v[22:25]
	ds_write_b128 v127, v[14:17] offset:4096
	ds_write_b128 v127, v[26:29] offset:8192
	ds_write_b128 v127, v[18:21] offset:12288
	v_pk_mul_f32 v[16:17], v[68:69], v[16:17]
	v_pk_mul_f32 v[14:15], v[32:33], v[14:15]
	ds_write_b128 v127, v[14:17] offset:16384
	ds_write_b128 v127, v[8:11] offset:20480
	s_and_saveexec_b64 s[14:15], s[4:5]
	v_pk_add_f32 v[4:5], v[4:5], v[6:7]
	s_nop 0
	v_pk_mul_f32 v[4:5], v[4:5], s[36:37] op_sel_hi:[1,0]
	ds_write_b64 v128, v[4:5]
	s_or_b64 exec, exec, s[14:15]
	v_add_u32_e32 v8, 16, v2
	v_mov_b64_e32 v[2:3], s[22:23]
	v_mad_i64_i32 v[2:3], s[14:15], v8, s56, v[2:3]
	v_mov_b32_e32 v83, v74
	v_lshl_add_u64 v[10:11], v[2:3], 0, v[82:83]
	v_add_co_u32_e32 v2, vcc, 0x1000, v10
	v_mov_b32_e32 v133, 0
	s_nop 0
	v_addc_co_u32_e32 v3, vcc, 0, v11, vcc
	v_add_co_u32_e32 v14, vcc, 0x2000, v10
	v_mov_b32_e32 v134, 0
	s_nop 0
	v_addc_co_u32_e32 v15, vcc, 0, v11, vcc
	global_load_dwordx2 v[6:7], v[10:11], off nt
	global_load_dwordx2 v[4:5], v[2:3], off nt
	s_nop 0
	global_load_dwordx2 v[2:3], v[14:15], off nt
	v_mov_b32_e32 v135, 0
	v_mov_b32_e32 v136, 0
	v_mov_b32_e32 v137, 0
	v_mov_b32_e32 v140, 0
	v_mov_b32_e32 v141, 0
	v_mov_b32_e32 v142, 0
	v_mov_b32_e32 v143, 0
	v_mov_b32_e32 v144, 0
	v_mov_b32_e32 v145, 0
	v_mov_b32_e32 v146, 0
	s_and_saveexec_b64 s[14:15], s[6:7]
	s_cbranch_execz .LBB0_1155
	v_add_co_u32_e32 v14, vcc, 0xffffd000, v10
	s_nop 1
	v_addc_co_u32_e32 v15, vcc, -1, v11, vcc
	v_add_co_u32_e32 v16, vcc, 0xffffe000, v10
	global_load_dwordx2 v[14:15], v[14:15], off offset:-1024 nt
	s_nop 0
	v_addc_co_u32_e32 v17, vcc, -1, v11, vcc
	v_add_co_u32_e32 v10, vcc, 0xfffff000, v10
	global_load_dwordx2 v[16:17], v[16:17], off offset:-1024 nt
	s_nop 0
	v_addc_co_u32_e32 v11, vcc, -1, v11, vcc
	global_load_dwordx2 v[10:11], v[10:11], off offset:-1024 nt
	s_waitcnt vmcnt(2)
	v_lshlrev_b32_e32 v133, 16, v14
	v_and_b32_e32 v134, 0xffff0000, v14
	v_lshlrev_b32_e32 v135, 16, v15
	v_and_b32_e32 v136, 0xffff0000, v15
	s_waitcnt vmcnt(1)
	v_lshlrev_b32_e32 v137, 16, v16
	v_and_b32_e32 v140, 0xffff0000, v16
	v_lshlrev_b32_e32 v141, 16, v17
	v_and_b32_e32 v142, 0xffff0000, v17
	s_waitcnt vmcnt(0)
	v_lshlrev_b32_e32 v143, 16, v10
	v_and_b32_e32 v144, 0xffff0000, v10
	v_lshlrev_b32_e32 v145, 16, v11
	v_and_b32_e32 v146, 0xffff0000, v11
.LBB0_1155:
	s_or_b64 exec, exec, s[14:15]
	v_ashrrev_i32_e32 v9, 31, v8
	v_lshlrev_b64 v[8:9], 12, v[8:9]
	v_lshl_add_u64 v[10:11], s[24:25], 0, v[8:9]
	v_lshl_add_u64 v[14:15], s[28:29], 0, v[8:9]
	v_lshl_add_u64 v[10:11], v[10:11], 0, v[82:83]
	v_lshl_add_u64 v[14:15], v[14:15], 0, v[82:83]
	global_load_dwordx2 v[10:11], v[10:11], off nt
	s_nop 0
	global_load_dwordx2 v[14:15], v[14:15], off nt
	v_lshl_add_u64 v[8:9], s[30:31], 0, v[8:9]
	v_lshl_add_u64 v[8:9], v[8:9], 0, v[82:83]
	global_load_dwordx2 v[86:87], v[8:9], off nt
	s_waitcnt vmcnt(4)
	v_lshlrev_b32_e32 v92, 16, v4
	v_and_b32_e32 v93, 0xffff0000, v4
	v_lshlrev_b32_e32 v94, 16, v5
	v_and_b32_e32 v95, 0xffff0000, v5
	s_waitcnt vmcnt(3)
	v_lshlrev_b32_e32 v96, 16, v2
	v_and_b32_e32 v97, 0xffff0000, v2
	v_lshlrev_b32_e32 v98, 16, v3
	v_and_b32_e32 v99, 0xffff0000, v3
	v_lshlrev_b32_e32 v88, 16, v6
	v_and_b32_e32 v89, 0xffff0000, v6
	v_lshlrev_b32_e32 v90, 16, v7
	v_and_b32_e32 v91, 0xffff0000, v7
	v_add_f32_e32 v147, v12, v13
	s_waitcnt vmcnt(2)
	v_lshlrev_b32_e32 v100, 16, v10
	s_waitcnt vmcnt(1)
	v_lshlrev_b32_e32 v2, 16, v14
	v_and_b32_e32 v3, 0xffff0000, v14
	v_lshlrev_b32_e32 v4, 16, v15
	v_and_b32_e32 v5, 0xffff0000, v15
	v_exp_f32_e64 v66, -v2
	v_exp_f32_e64 v67, -v3
	v_exp_f32_e64 v68, -v4
	v_exp_f32_e64 v69, -v5
	v_and_b32_e32 v101, 0xffff0000, v10
	v_lshlrev_b32_e32 v102, 16, v11
	v_and_b32_e32 v103, 0xffff0000, v11

.LBB0_1164:
	s_cmpk_gt_u32 s53, 0x7e
	v_mov_b32_e32 v83, v69
	v_mov_b32_e32 v122, v68
	v_mov_b32_e32 v123, v67
	v_mov_b32_e32 v124, v66
	v_mov_b32_e32 v125, v103
	v_mov_b32_e32 v150, v102
	v_mov_b32_e32 v153, v101
	v_mov_b32_e32 v151, v100
	v_mov_b32_e32 v149, v146
	v_mov_b32_e32 v152, v145
	v_mov_b32_e32 v154, v144
	v_mov_b32_e32 v155, v143
	v_mov_b32_e32 v156, v142
	v_mov_b32_e32 v157, v141
	v_mov_b32_e32 v158, v140
	v_mov_b32_e32 v159, v137
	v_mov_b32_e32 v160, v136
	v_mov_b32_e32 v161, v135
	v_mov_b32_e32 v162, v134
	v_mov_b32_e32 v164, v133
	v_mov_b32_e32 v163, v99
	v_mov_b32_e32 v165, v98
	v_mov_b32_e32 v166, v97
	v_mov_b32_e32 v167, v96
	v_mov_b32_e32 v168, v95
	v_mov_b32_e32 v169, v94
	v_mov_b32_e32 v170, v93
	v_mov_b32_e32 v171, v92
	v_mov_b32_e32 v172, v91
	v_mov_b32_e32 v173, v90
	v_mov_b32_e32 v174, v89
	v_mov_b32_e32 v175, v88
	v_mov_b64_e32 v[120:121], v[84:85]
	v_mov_b32_e32 v75, v147
	s_waitcnt vmcnt(0)
	v_mov_b64_e32 v[118:119], v[86:87]
	s_cbranch_scc1 .LBB0_1172
	v_sub_f32_e32 v19, v136, v91
	v_sub_f32_e32 v18, v135, v90
	v_sub_f32_e32 v21, v134, v89
	v_sub_f32_e32 v20, v133, v88
	v_pk_fma_f32 v[32:33], v[50:51], v[20:21], v[88:89]
	v_pk_fma_f32 v[150:151], v[52:53], v[18:19], v[90:91]
	v_sub_f32_e32 v19, v140, v93
	v_sub_f32_e32 v18, v137, v92
	v_sub_f32_e32 v21, v142, v95
	v_sub_f32_e32 v20, v141, v94
	v_pk_fma_f32 v[20:21], v[48:49], v[20:21], v[94:95]
	v_pk_fma_f32 v[18:19], v[46:47], v[18:19], v[92:93]
	v_sub_f32_e32 v23, v144, v97
	v_sub_f32_e32 v22, v143, v96
	v_sub_f32_e32 v25, v146, v99
	v_sub_f32_e32 v24, v145, v98
	v_pk_fma_f32 v[26:27], v[44:45], v[24:25], v[98:99]
	v_pk_fma_f32 v[24:25], v[42:43], v[22:23], v[96:97]
	v_pk_mul_f32 v[22:23], v[62:63], v[18:19]
	v_pk_mul_f32 v[118:119], v[64:65], v[20:21]
	v_pk_mul_f32 v[30:31], v[22:23], v[22:23]
	v_pk_mul_f32 v[28:29], v[118:119], v[118:119]
	s_xor_b32 s26, s62, 1
	v_pk_mov_b32 v[120:121], v[30:31], v[28:29] op_sel:[1,0]
	v_mov_b32_e32 v31, v29
	v_pk_add_f32 v[28:29], v[120:121], v[30:31]
	v_pk_add_f32 v[30:31], v[102:103], -1.0 op_sel_hi:[1,0]
	v_add_f32_e32 v28, v28, v29
	v_pk_fma_f32 v[30:31], v[60:61], v[30:31], 1.0 op_sel_hi:[1,1,0]
	s_mul_i32 s27, s26, 0x6000
	v_add_f32_dpp v28, v28, v28 quad_perm:[1,0,3,2] row_mask:0xf bank_mask:0xf bound_ctrl:1
	v_pk_mul_f32 v[30:31], v[30:31], v[20:21]
	s_nop 0
	v_add_f32_dpp v28, v28, v28 quad_perm:[2,3,0,1] row_mask:0xf bank_mask:0xf bound_ctrl:1
	s_nop 1
	v_add_f32_dpp v28, v28, v28 row_half_mirror row_mask:0xf bank_mask:0xf bound_ctrl:1
	s_nop 1
	v_add_f32_dpp v28, v28, v28 row_mirror row_mask:0xf bank_mask:0xf bound_ctrl:1
	v_mul_f32_e32 v29, 0x4f800000, v28
	v_cmp_gt_f32_e32 vcc, s60, v28
	s_nop 1
	v_cndmask_b32_e32 v75, v28, v29, vcc
	v_sqrt_f32_e32 v83, v75
	v_pk_add_f32 v[28:29], v[100:101], -1.0 op_sel_hi:[1,0]
	v_add_u32_e32 v120, -1, v83
	v_fma_f32 v121, -v120, v83, v75
	v_cmp_ge_f32_e64 s[14:15], 0, v121
	v_add_u32_e32 v121, 1, v83
	v_pk_fma_f32 v[28:29], v[58:59], v[28:29], 1.0 op_sel_hi:[1,1,0]
	v_cndmask_b32_e64 v120, v83, v120, s[14:15]
	v_fma_f32 v83, -v121, v83, v75
	v_cmp_lt_f32_e64 s[14:15], 0, v83
	v_pk_mul_f32 v[28:29], v[28:29], v[18:19]
	s_nop 0
	v_cndmask_b32_e64 v83, v120, v121, s[14:15]
	v_mul_f32_e32 v120, 0x37800000, v83
	v_cndmask_b32_e32 v83, v83, v120, vcc
	v_cmp_class_f32_e32 vcc, v75, v71
	v_pk_mul_f32 v[152:153], v[32:33], v[28:29]
	s_nop 0
	v_cndmask_b32_e32 v75, v83, v75, vcc
	v_max_f32_e32 v75, 0x2b8cbccc, v75
	v_div_scale_f32 v83, s[14:15], v75, v75, -1.0
	v_rcp_f32_e32 v120, v83
	v_mov_b32_e32 v155, v152
	v_fma_f32 v18, -v83, v120, 1.0
	v_fmac_f32_e32 v120, v18, v120
	v_div_scale_f32 v18, vcc, -1.0, v75, -1.0
	v_mul_f32_e32 v19, v18, v120
	v_fma_f32 v20, -v83, v19, v18
	v_fmac_f32_e32 v19, v20, v120
	v_fma_f32 v18, -v83, v19, v18
	v_div_fmas_f32 v18, v18, v120, v19
	v_div_fixup_f32 v18, v18, v75, -1.0
	v_pk_mul_f32 v[120:121], v[118:119], v[18:19] op_sel_hi:[1,0]
	v_pk_mul_f32 v[118:119], v[22:23], v[18:19] op_sel_hi:[1,0]
	v_pk_mul_f32 v[124:125], v[120:121], v[102:103] neg_lo:[1,0] neg_hi:[1,0]
	v_pk_mul_f32 v[122:123], v[118:119], v[100:101] neg_lo:[1,0] neg_hi:[1,0]
	v_pk_mul_f32 v[18:19], v[150:151], v[124:125]
	v_pk_mul_f32 v[20:21], v[32:33], v[122:123]
	v_pk_mul_f32 v[22:23], v[150:151], v[30:31]
	v_mov_b32_e32 v154, v20
	v_mov_b32_e32 v20, v21
	v_mov_b32_e32 v21, v153
	v_pk_add_f32 v[20:21], v[154:155], v[20:21]
	v_mov_b32_e32 v154, v18
	v_mov_b32_e32 v155, v22
	v_mov_b32_e32 v18, v19
	v_mov_b32_e32 v19, v23
	v_pk_add_f32 v[18:19], v[154:155], v[18:19]
	v_pk_mul_f32 v[22:23], v[56:57], v[22:23]
	v_pk_add_f32 v[18:19], v[20:21], v[18:19]
	v_mov_b32_e32 v20, 0
	v_mov_b32_e32 v21, 0
	v_pk_mul_f32 v[152:153], v[54:55], v[152:153]
	v_mov_b32_dpp v20, v18 quad_perm:[1,0,3,2] row_mask:0xf bank_mask:0xf
	v_mov_b32_dpp v21, v19 quad_perm:[1,0,3,2] row_mask:0xf bank_mask:0xf
	v_pk_add_f32 v[18:19], v[18:19], v[20:21]
	v_mov_b32_e32 v20, 0
	v_mov_b32_e32 v21, 0
	v_add_f32_e32 v75, v152, v153
	v_add_f32_e32 v22, v22, v23
	v_mov_b32_dpp v20, v18 quad_perm:[2,3,0,1] row_mask:0xf bank_mask:0xf
	v_mov_b32_dpp v21, v19 quad_perm:[2,3,0,1] row_mask:0xf bank_mask:0xf
	v_add_f32_e32 v22, v75, v22
	v_pk_add_f32 v[18:19], v[18:19], v[20:21]
	v_mov_b32_e32 v20, 0
	v_mov_b32_e32 v21, 0
	v_add_f32_dpp v22, v22, v22 quad_perm:[1,0,3,2] row_mask:0xf bank_mask:0xf bound_ctrl:1
	v_mov_b32_dpp v20, v18 row_half_mirror row_mask:0xf bank_mask:0xf
	v_mov_b32_dpp v21, v19 row_half_mirror row_mask:0xf bank_mask:0xf
	v_add_f32_dpp v22, v22, v22 quad_perm:[2,3,0,1] row_mask:0xf bank_mask:0xf bound_ctrl:1
	v_pk_add_f32 v[18:19], v[18:19], v[20:21]
	v_mov_b32_e32 v20, 0
	v_mov_b32_e32 v21, 0
	v_add_f32_dpp v22, v22, v22 row_half_mirror row_mask:0xf bank_mask:0xf bound_ctrl:1
	v_mov_b32_e32 v23, 0
	v_add_u32_e32 v75, s27, v127
	v_mov_b32_dpp v20, v18 row_mirror row_mask:0xf bank_mask:0xf
	v_mov_b32_dpp v21, v19 row_mirror row_mask:0xf bank_mask:0xf
	v_mov_b32_dpp v23, v22 row_mirror row_mask:0xf bank_mask:0xf
	ds_write_b128 v75, v[118:121]
	ds_write_b128 v75, v[66:69] offset:4096
	ds_write_b128 v75, v[122:125] offset:8192
	ds_write_b128 v75, v[28:31] offset:12288
	v_pk_mul_f32 v[30:31], v[68:69], v[150:151]
	v_pk_mul_f32 v[28:29], v[66:67], v[32:33]
	ds_write_b128 v75, v[28:31] offset:16384
	ds_write_b128 v75, v[24:27] offset:20480
	s_and_saveexec_b64 s[14:15], s[4:5]
	v_pk_add_f32 v[18:19], v[18:19], v[20:21]
	v_lshl_add_u32 v24, s26, 7, v128
	v_pk_mul_f32 v[18:19], v[18:19], s[36:37] op_sel_hi:[1,0]
	ds_write_b64 v24, v[18:19]
	s_or_b64 exec, exec, s[14:15]
	s_cmpk_eq_i32 s41, 0x7e0
	v_mov_b32_e32 v83, v69
	v_mov_b32_e32 v122, v68
	v_mov_b32_e32 v123, v67
	v_mov_b32_e32 v124, v66
	v_mov_b32_e32 v125, v103
	v_mov_b32_e32 v150, v102
	v_mov_b32_e32 v153, v101
	v_mov_b32_e32 v151, v100
	v_mov_b32_e32 v149, v146
	v_mov_b32_e32 v152, v145
	v_mov_b32_e32 v154, v144
	v_mov_b32_e32 v155, v143
	v_mov_b32_e32 v156, v142
	v_mov_b32_e32 v157, v141
	v_mov_b32_e32 v158, v140
	v_mov_b32_e32 v159, v137
	v_mov_b32_e32 v160, v136
	v_mov_b32_e32 v161, v135
	v_mov_b32_e32 v162, v134
	v_mov_b32_e32 v164, v133
	v_mov_b32_e32 v163, v99
	v_mov_b32_e32 v165, v98
	v_mov_b32_e32 v166, v97
	v_mov_b32_e32 v167, v96
	v_mov_b32_e32 v168, v95
	v_mov_b32_e32 v169, v94
	v_mov_b32_e32 v170, v93
	v_mov_b32_e32 v171, v92
	v_mov_b32_e32 v172, v91
	v_mov_b32_e32 v173, v90
	v_mov_b32_e32 v174, v89
	v_mov_b32_e32 v175, v88
	v_mov_b64_e32 v[118:119], v[86:87]
	s_cbranch_scc1 .LBB0_1171
	v_add3_u32 v18, v70, s41, 32
	v_mov_b32_e32 v75, v74
	v_cmp_gt_i32_e32 vcc, s61, v18
	v_mov_b32_e32 v125, 0
	v_mov_b32_e32 v83, 0
	v_mov_b32_e32 v122, 0
	v_mov_b32_e32 v123, 0
	v_mov_b32_e32 v124, 0
	v_mov_b32_e32 v150, 0
	v_mov_b32_e32 v153, 0
	v_mov_b32_e32 v151, 0
	v_mov_b32_e32 v149, 0
	v_mov_b32_e32 v152, 0
	v_mov_b32_e32 v154, 0
	v_mov_b32_e32 v155, 0
	v_mov_b32_e32 v156, 0
	v_mov_b32_e32 v157, 0
	v_mov_b32_e32 v158, 0
	v_mov_b32_e32 v159, 0
	v_mov_b32_e32 v160, 0
	v_mov_b32_e32 v161, 0
	v_mov_b32_e32 v162, 0
	v_mov_b32_e32 v164, 0
	v_mov_b32_e32 v163, 0
	v_mov_b32_e32 v165, 0
	v_mov_b32_e32 v166, 0
	v_mov_b32_e32 v167, 0
	v_mov_b32_e32 v168, 0
	v_mov_b32_e32 v169, 0
	v_mov_b32_e32 v170, 0
	v_mov_b32_e32 v171, 0
	v_mov_b32_e32 v172, 0
	v_mov_b32_e32 v173, 0
	v_mov_b32_e32 v174, 0
	v_mov_b32_e32 v175, 0
	v_mov_b64_e32 v[118:119], v[74:75]
	s_and_saveexec_b64 s[14:15], vcc
	s_cbranch_execz .LBB0_1170
	v_add_u32_e32 v18, s41, v148
	v_mad_i64_i32 v[20:21], s[26:27], v18, s56, v[110:111]
	v_add_co_u32_e32 v24, vcc, 0x1000, v20
	v_ashrrev_i32_e32 v19, 31, v18
	s_nop 0
	v_addc_co_u32_e32 v25, vcc, 0, v21, vcc
	v_add_co_u32_e32 v28, vcc, 0x2000, v20
	global_load_dwordx2 v[26:27], v[20:21], off nt
	s_nop 0
	global_load_dwordx2 v[24:25], v[24:25], off nt
	v_addc_co_u32_e32 v29, vcc, 0, v21, vcc
	v_add_co_u32_e32 v30, vcc, 0xfffff000, v20
	v_lshlrev_b64 v[18:19], 12, v[18:19]
	s_nop 0
	v_addc_co_u32_e32 v31, vcc, -1, v21, vcc
	v_add_co_u32_e32 v32, vcc, s59, v20
	v_lshl_add_u64 v[118:119], v[112:113], 0, v[18:19]
	s_nop 0
	v_addc_co_u32_e32 v33, vcc, -1, v21, vcc
	v_add_co_u32_e32 v20, vcc, s57, v20
	v_lshl_add_u64 v[120:121], v[114:115], 0, v[18:19]
	s_nop 0
	v_addc_co_u32_e32 v21, vcc, -1, v21, vcc
	global_load_dwordx2 v[28:29], v[28:29], off nt
	s_nop 0
	global_load_dwordx2 v[30:31], v[30:31], off offset:-1024 nt
	v_lshl_add_u64 v[18:19], v[116:117], 0, v[18:19]
	global_load_dwordx2 v[32:33], v[32:33], off offset:-1024 nt
	s_waitcnt vmcnt(4)
	v_lshlrev_b32_e32 v175, 16, v26
	global_load_dwordx2 v[20:21], v[20:21], off offset:-1024 nt
	s_nop 0
	global_load_dwordx2 v[176:177], v[118:119], off nt
	s_nop 0
	global_load_dwordx2 v[120:121], v[120:121], off nt
	v_and_b32_e32 v174, 0xffff0000, v26
	global_load_dwordx2 v[118:119], v[18:19], off nt
	v_lshlrev_b32_e32 v173, 16, v27
	v_and_b32_e32 v172, 0xffff0000, v27
	s_waitcnt vmcnt(7)
	v_lshlrev_b32_e32 v171, 16, v24
	v_and_b32_e32 v170, 0xffff0000, v24
	v_lshlrev_b32_e32 v169, 16, v25
	v_and_b32_e32 v168, 0xffff0000, v25
	s_waitcnt vmcnt(6)
	v_lshlrev_b32_e32 v167, 16, v28
	v_and_b32_e32 v166, 0xffff0000, v28
	v_lshlrev_b32_e32 v165, 16, v29
	v_and_b32_e32 v163, 0xffff0000, v29
	s_waitcnt vmcnt(5)
	v_lshlrev_b32_e32 v155, 16, v30
	v_and_b32_e32 v154, 0xffff0000, v30
	v_lshlrev_b32_e32 v152, 16, v31
	v_and_b32_e32 v149, 0xffff0000, v31
	s_waitcnt vmcnt(4)
	v_lshlrev_b32_e32 v159, 16, v32
	v_and_b32_e32 v158, 0xffff0000, v32
	v_lshlrev_b32_e32 v157, 16, v33
	v_and_b32_e32 v156, 0xffff0000, v33
	s_waitcnt vmcnt(3)
	v_lshlrev_b32_e32 v164, 16, v20
	v_and_b32_e32 v162, 0xffff0000, v20
	v_lshlrev_b32_e32 v161, 16, v21
	v_and_b32_e32 v160, 0xffff0000, v21
	s_waitcnt vmcnt(1)
	v_lshlrev_b32_e32 v18, 16, v120
	v_and_b32_e32 v19, 0xffff0000, v120
	v_lshlrev_b32_e32 v20, 16, v121
	v_and_b32_e32 v21, 0xffff0000, v121
	v_exp_f32_e64 v124, -v18
	v_exp_f32_e64 v123, -v19
	v_exp_f32_e64 v122, -v20
	v_exp_f32_e64 v83, -v21
	v_lshlrev_b32_e32 v151, 16, v176
	v_and_b32_e32 v153, 0xffff0000, v176
	v_lshlrev_b32_e32 v150, 16, v177
	v_and_b32_e32 v125, 0xffff0000, v177
